# LayerNorm phase row loop hand-written: gamma/beta hoisted, all loads of a row in flight under one wait; leaner ring loop for mixer B (scalar-base LDS-DMA)
# speedup vs baseline: 1.1216x; 1.0378x over previous
; template <int NS>
; DI void attn_item(const Params& p, int layer, char* smem, VBC& vc, int b, int hq, int qblk) {
;     ...
;     for (int it = 0; it < ntiles; ++it) {
;         const int buf = it & 1;
;         if (it + 1 < ntiles) dma_tile(it + 1, buf ^ 1);
.LBB0_941:
	s_cmp_eq_u32 s46, 1
	s_cbranch_scc0 .Lorig_941B
	s_and_b64 vcc, exec, s[14:15]
	s_cbranch_vccnz .Lr_takeover

; template <int NS>
; DI void attn_item(const Params& p, int layer, char* smem, VBC& vc, int b, int hq, int qblk) {
;     ...
;         auto qk = [&](const int m, f32x16 (&s)[2]) {
; #pragma unroll
;             for (int kt2 = 0; kt2 < 2; ++kt2)
; #pragma unroll
;                 for (int e = 0; e < 16; ++e) s[kt2][e] = 0.f;
;             __builtin_amdgcn_s_setprio(1);
; #pragma unroll
;             for (int ks = 0; ks < NKS; ++ks)
; #pragma unroll
;                 for (int kt2 = 0; kt2 < 2; ++kt2) s[kt2] = MFMA(ld8(cK + (kt2 * 32 + r) * 64 + (((m * DQK + ks * 16)) ^ hs16)), qf[m][ks], s[kt2]);
; #pragma unroll
;             for (int kt2 = 0; kt2 < 2; ++kt2) { uint4 qa4 = {qaug[m], 0u, 0u, 0u}; s[kt2] = MFMA(kones, __builtin_bit_cast(bf16x8, qa4), s[kt2]); }
;             __builtin_amdgcn_s_setprio(0);
;         };
;         auto softmax = [&](const int m, f32x16 (&s)[2], bf16x8 (&pf)[2][2]) {
;             const bool fixed = fast && it > 0;
;             if (NS == 1 && is_lat) {
; #pragma unroll
;                 for (int kt2 = 0; kt2 < 2; ++kt2)
; #pragma unroll
;                     for (int e = 0; e < 16; ++e) {
;                         int d = kpos0 + kt2 * 32 + crow(e, h) - qpos;
;                         if (d > 128 || d < -128) s[kt2][e] = -1e30f;
;                     }
;             }
;             if (fixed) {
;                 float ls = 0.f;
; #pragma unroll
;                 for (int kt2 = 0; kt2 < 2; ++kt2)
; #pragma unroll
;                     for (int e = 0; e < 16; ++e) { const float pv = __builtin_amdgcn_exp2f(s[kt2][e]); s[kt2][e] = pv; ls += pv; }
;                 lrun[m] += ls;
;             } else {
;                 float tmax = -1e30f;
;     #pragma unroll
;                 for (int kt2 = 0; kt2 < 2; ++kt2)
;     #pragma unroll
;                     for (int e = 0; e < 16; ++e) tmax = fmaxf(tmax, s[kt2][e]);
;                 tmax = fmaxf(tmax, __shfl_xor(tmax, 32));
;                 float mnew = fmaxf(mrun[m], tmax * cexp);
;                 if (fast) mnew = bf2f(f2bf(mnew));
;                 const float alpha = __builtin_amdgcn_exp2f(mrun[m] - mnew);
;                 mrun[m] = mnew;
;                 f32x2 ls2 = {0.f, 0.f};
;                 const f32x2 cc2 = {cexp, cexp}, mm2 = {-mnew, -mnew};
;     #pragma unroll
;                 for (int kt2 = 0; kt2 < 2; ++kt2)
;     #pragma unroll
.LBB0_945:
	s_cmp_eq_u32 s46, 0
	s_cbranch_scc1 .Lr_iter0
.Lorig_945B:
	s_setprio 1
	v_lshl_add_u32 v9, s17, 1, v248
	v_lshl_add_u32 v6, v201, 1, v9
	ds_read_b128 v[10:13], v6
	v_lshl_add_u32 v5, v245, 1, v9
	s_mov_b32 s54, s53
	s_mov_b32 s55, s53
	v_mov_b32_e32 v2, v1
	v_mov_b32_e32 v3, v1
	s_waitcnt lgkmcnt(0)
	v_mfma_f32_32x32x16_bf16 v[96:111], v[10:13], v[176:179], 0
	ds_read_b128 v[10:13], v6 offset:4096
	s_waitcnt lgkmcnt(0)
	v_mfma_f32_32x32x16_bf16 v[80:95], v[10:13], v[176:179], 0
	ds_read_b128 v[10:13], v5
	s_waitcnt lgkmcnt(0)
	v_mfma_f32_32x32x16_bf16 v[96:111], v[10:13], v[180:183], v[96:111]
	ds_read_b128 v[10:13], v5 offset:4096
	s_waitcnt lgkmcnt(0)
	v_mfma_f32_32x32x16_bf16 v[80:95], v[10:13], v[180:183], v[80:95]
	v_mov_b64_e32 v[10:11], s[52:53]
	v_mov_b64_e32 v[12:13], s[54:55]
	s_nop 1
	v_mfma_f32_32x32x16_bf16 v[96:111], v[10:13], v[0:3], v[96:111]
	v_mfma_f32_32x32x16_bf16 v[80:95], v[10:13], v[0:3], v[80:95]
	s_setprio 0
	s_cmp_eq_u32 s46, 0
	s_cselect_b64 s[0:1], -1, 0
	s_xor_b64 s[48:49], s[14:15], -1
	s_or_b64 s[0:1], s[48:49], s[0:1]
	s_mov_b64 s[16:17], -1
	s_and_b64 vcc, exec, s[0:1]
	s_cbranch_vccz .LBB0_949
	s_nop 2
	v_max3_f32 v2, v96, s68, v97
	v_max3_f32 v2, v2, v98, v99
	v_max3_f32 v2, v2, v100, v101
	v_max3_f32 v2, v2, v102, v103
	v_max3_f32 v2, v2, v104, v105
	v_max3_f32 v2, v2, v106, v107
	v_max3_f32 v2, v2, v108, v109
	v_max3_f32 v2, v2, v110, v111
	v_max3_f32 v2, v2, v80, v81
	v_max3_f32 v2, v2, v82, v83
	v_max3_f32 v2, v2, v84, v85
	v_max3_f32 v2, v2, v86, v87
	v_and_b32_e32 v8, 64, v237
	v_max3_f32 v2, v2, v88, v89
	v_xor_b32_e32 v3, 32, v237
	v_add_u32_e32 v8, 64, v8
	v_max3_f32 v2, v2, v90, v91
	v_cmp_lt_i32_e32 vcc, v3, v8
	v_max3_f32 v2, v2, v92, v93
	v_max3_f32 v2, v2, v94, v95
	v_cndmask_b32_e32 v3, v237, v3, vcc
	v_lshlrev_b32_e32 v3, 2, v3
	ds_bpermute_b32 v3, v3, v2
	v_mov_b64_e32 v[142:143], v[46:47]
	v_mov_b64_e32 v[126:127], v[78:79]
	v_mov_b64_e32 v[140:141], v[44:45]
	v_mov_b64_e32 v[138:139], v[42:43]
	s_waitcnt lgkmcnt(0)
	v_max3_f32 v2, v7, v2, v3
	v_cvt_pk_bf16_f32 v3, v2, s0
	v_lshlrev_b32_e32 v3, 16, v3
	v_cndmask_b32_e64 v226, v2, v3, s[14:15]
	v_sub_f32_e32 v2, v7, v226
	v_exp_f32_e32 v2, v2
	v_mov_b64_e32 v[136:137], v[40:41]
	v_mov_b64_e32 v[134:135], v[38:39]
	v_mov_b64_e32 v[132:133], v[36:37]
	v_mov_b64_e32 v[130:131], v[34:35]
	v_mov_b64_e32 v[128:129], v[32:33]
	v_cmp_neq_f32_e32 vcc, 1.0, v2
	v_mov_b64_e32 v[124:125], v[76:77]
	v_mov_b64_e32 v[122:123], v[74:75]
	v_mov_b64_e32 v[120:121], v[72:73]
	v_mov_b64_e32 v[118:119], v[70:71]
	v_mov_b64_e32 v[116:117], v[68:69]
	v_mov_b64_e32 v[114:115], v[66:67]
	v_mov_b64_e32 v[112:113], v[64:65]
	s_cbranch_vccz .LBB0_948
	v_pk_mul_f32 v[126:127], v[78:79], v[2:3] op_sel_hi:[1,0]
	v_pk_mul_f32 v[124:125], v[76:77], v[2:3] op_sel_hi:[1,0]
	v_pk_mul_f32 v[122:123], v[74:75], v[2:3] op_sel_hi:[1,0]
	v_pk_mul_f32 v[120:121], v[72:73], v[2:3] op_sel_hi:[1,0]
	v_pk_mul_f32 v[118:119], v[70:71], v[2:3] op_sel_hi:[1,0]
	v_pk_mul_f32 v[116:117], v[68:69], v[2:3] op_sel_hi:[1,0]
	v_pk_mul_f32 v[114:115], v[66:67], v[2:3] op_sel_hi:[1,0]
	v_pk_mul_f32 v[112:113], v[64:65], v[2:3] op_sel_hi:[1,0]
	v_pk_mul_f32 v[142:143], v[46:47], v[2:3] op_sel_hi:[1,0]
	v_pk_mul_f32 v[140:141], v[44:45], v[2:3] op_sel_hi:[1,0]
	v_pk_mul_f32 v[138:139], v[42:43], v[2:3] op_sel_hi:[1,0]
	v_pk_mul_f32 v[136:137], v[40:41], v[2:3] op_sel_hi:[1,0]
	v_pk_mul_f32 v[134:135], v[38:39], v[2:3] op_sel_hi:[1,0]
	v_pk_mul_f32 v[132:133], v[36:37], v[2:3] op_sel_hi:[1,0]
	v_pk_mul_f32 v[130:131], v[34:35], v[2:3] op_sel_hi:[1,0]
	v_pk_mul_f32 v[128:129], v[32:33], v[2:3] op_sel_hi:[1,0]

; template <int NS>
; DI void attn_item(const Params& p, int layer, char* smem, VBC& vc, int b, int hq, int qblk) {
;     ...
;     auto tile_ptrs = [&](int it, const u16*& kp, const u16*& vp) {
;         if (it < lat1 - lat0) { int kt = lat0 + it; kp = P + (size_t)(b * SEQ + kt * 64) * PC + kcol; vp = VT + kt * 64; }
;         else { int c = it - (lat1 - lat0); kp = P + (size_t)(NLAT + b * CTXL + c * 64) * PC + kcol; vp = VT + SEQ + c * 64; }
;     };
;     auto dma_tile = [&](int it, int st) {
;         const u16 *kp, *vp; tile_ptrs(it, kp, vp);
; #pragma unroll
;         for (int i = 0; i < 2; ++i) {
;             const int row = wave4 * 16 + i * 8 + drow;
;             const int chunk = dslot ^ ((row >> 1) & 7);
;             lds_u32* dk = (lds_u32*)(sK + st * 8192 + (wave4 * 16 + i * 8) * 64);
;             lds_u32* dv = (lds_u32*)(sK + st * 8192 + 4096 + (wave4 * 16 + i * 8) * 64);
;             __builtin_amdgcn_global_load_lds((const unsigned*)(kp + (size_t)row * PC + chunk * 8), dk, 16, 0, 0);
;             __builtin_amdgcn_global_load_lds((const unsigned*)(vp + (size_t)row * KVS + chunk * 8), dv, 16, 0, 0);
;         }
;     };
.Lr_iter0:
	s_and_b64 vcc, exec, s[14:15]
	s_cbranch_vccz .Lorig_945B
	v_readlane_b32 s0, v252, 21
	s_lshr_b32 s0, s0, 4
	s_add_i32 s0, s0, s33
	s_add_i32 s16, s0, 0x10000
	v_mov_b32_e32 v2, s16
	v_mov_b32_e32 v3, 0
	s_mov_b64 exec, 1
	ds_write_b32 v2, v3
	s_mov_b64 exec, -1
	s_branch .Lorig_945B
.Lr_takeover:
	v_readlane_b32 s0, v252, 21
	s_lshr_b32 s0, s0, 4
	s_add_i32 s0, s0, s33
	s_add_i32 s16, s0, 0x10000
	v_lshl_add_u32 v5, v241, 1, s33
	v_lshl_add_u32 v6, v243, 1, s33
	s_nop 0
	v_readfirstlane_b32 s98, v5
	v_readfirstlane_b32 s99, v6
	s_mov_b32 s47, 2
	s_mov_b32 s55, 0x8000
	s_cmp_lt_u32 s47, s21
	s_cselect_b64 s[0:1], -1, 0
	s_sub_i32 s17, s47, s21
	s_min_u32 s17, s47, s17
	s_and_b64 s[0:1], s[0:1], exec
	s_cselect_b32 s0, s20, s27
	s_cselect_b32 s1, s25, s41
	s_cselect_b32 s48, s24, s40
	s_lshl_b32 s49, s17, 6
	s_add_i32 s49, s49, s0
	s_lshl_b32 s0, s17, 7
	s_add_u32 s0, s48, s0
	s_addc_u32 s1, s1, 0
	s_mul_hi_i32 s17, s49, 0x1a80
	s_mulk_i32 s49, 0x1a80
	s_add_u32 s48, s42, s49
	s_addc_u32 s49, s43, s17
	v_add_u32_e32 v2, v206, v222
	s_add_i32 m0, s98, s55
	v_add_u32_e32 v3, v208, v222
	global_load_lds_dwordx4 v2, s[48:49]
	s_add_i32 m0, m0, 0x2000
	v_add_u32_e32 v5, v210, v224
	global_load_lds_dwordx4 v3, s[0:1]
	s_add_i32 m0, s99, s55
	v_add_u32_e32 v6, v212, v224
	global_load_lds_dwordx4 v5, s[48:49]
	s_add_i32 m0, m0, 0x2000
	s_nop 0
	global_load_lds_dwordx4 v6, s[0:1]
	s_mov_b32 s47, 3
	s_mov_b32 s55, 0xc000
	s_cmp_lt_u32 s47, s21
	s_cselect_b64 s[0:1], -1, 0
	s_sub_i32 s17, s47, s21
	s_min_u32 s17, s47, s17
	s_and_b64 s[0:1], s[0:1], exec
	s_cselect_b32 s0, s20, s27
	s_cselect_b32 s1, s25, s41
	s_cselect_b32 s48, s24, s40
	s_lshl_b32 s49, s17, 6
	s_add_i32 s49, s49, s0
	s_lshl_b32 s0, s17, 7
	s_add_u32 s0, s48, s0
	s_addc_u32 s1, s1, 0
	s_mul_hi_i32 s17, s49, 0x1a80
	s_mulk_i32 s49, 0x1a80
	s_add_u32 s48, s42, s49
	s_addc_u32 s49, s43, s17
	v_add_u32_e32 v2, v206, v222
	s_add_i32 m0, s98, s55
	v_add_u32_e32 v3, v208, v222
	global_load_lds_dwordx4 v2, s[48:49]
	s_add_i32 m0, m0, 0x2000
	v_add_u32_e32 v5, v210, v224
	global_load_lds_dwordx4 v3, s[0:1]
	s_add_i32 m0, s99, s55
	v_add_u32_e32 v6, v212, v224
	global_load_lds_dwordx4 v5, s[48:49]
	s_add_i32 m0, m0, 0x2000
	s_nop 0
	global_load_lds_dwordx4 v6, s[0:1]
	s_movk_i32 s17, 0x2000
	s_branch .Lr_body
.Lr_loop:
	s_waitcnt vmcnt(0)
	s_add_i32 s1, s46, -1
	v_mov_b32_e32 v2, s16
	v_mov_b32_e32 v3, s1
	s_mov_b64 exec, 1
	ds_write_b32 v2, v3
	s_mov_b64 exec, -1
	s_add_i32 s0, s33, 0x10000
	v_mov_b32_e32 v6, s0
	s_add_i32 s1, s46, -2
	s_max_i32 s1, s1, 1

; template <int NS>
; DI void attn_item(const Params& p, int layer, char* smem, VBC& vc, int b, int hq, int qblk) {
;     ...
;     auto tile_ptrs = [&](int it, const u16*& kp, const u16*& vp) {
;         if (it < lat1 - lat0) { int kt = lat0 + it; kp = P + (size_t)(b * SEQ + kt * 64) * PC + kcol; vp = VT + kt * 64; }
;         else { int c = it - (lat1 - lat0); kp = P + (size_t)(NLAT + b * CTXL + c * 64) * PC + kcol; vp = VT + SEQ + c * 64; }
;     };
;     auto dma_tile = [&](int it, int st) {
;         const u16 *kp, *vp; tile_ptrs(it, kp, vp);
; #pragma unroll
;         for (int i = 0; i < 2; ++i) {
;             const int row = wave4 * 16 + i * 8 + drow;
;             const int chunk = dslot ^ ((row >> 1) & 7);
;             lds_u32* dk = (lds_u32*)(sK + st * 8192 + (wave4 * 16 + i * 8) * 64);
;             lds_u32* dv = (lds_u32*)(sK + st * 8192 + 4096 + (wave4 * 16 + i * 8) * 64);
;             __builtin_amdgcn_global_load_lds((const unsigned*)(kp + (size_t)row * PC + chunk * 8), dk, 16, 0, 0);
;             __builtin_amdgcn_global_load_lds((const unsigned*)(vp + (size_t)row * KVS + chunk * 8), dv, 16, 0, 0);
;         }
;     };
;     ...
;         auto qk = [&](const int m, f32x16 (&s)[2]) {
; #pragma unroll
;             for (int kt2 = 0; kt2 < 2; ++kt2)
; #pragma unroll
;                 for (int e = 0; e < 16; ++e) s[kt2][e] = 0.f;
;             __builtin_amdgcn_s_setprio(1);
; #pragma unroll
;             for (int ks = 0; ks < NKS; ++ks)
; #pragma unroll
;                 for (int kt2 = 0; kt2 < 2; ++kt2) s[kt2] = MFMA(ld8(cK + (kt2 * 32 + r) * 64 + (((m * DQK + ks * 16)) ^ hs16)), qf[m][ks], s[kt2]);
; #pragma unroll
;             for (int kt2 = 0; kt2 < 2; ++kt2) { uint4 qa4 = {qaug[m], 0u, 0u, 0u}; s[kt2] = MFMA(kones, __builtin_bit_cast(bf16x8, qa4), s[kt2]); }
;             __builtin_amdgcn_s_setprio(0);
;         };
;         auto softmax = [&](const int m, f32x16 (&s)[2], bf16x8 (&pf)[2][2]) {
;             const bool fixed = fast && it > 0;
;             if (NS == 1 && is_lat) {
; #pragma unroll
;                 for (int kt2 = 0; kt2 < 2; ++kt2)
; #pragma unroll
;                     for (int e = 0; e < 16; ++e) {
;                         int d = kpos0 + kt2 * 32 + crow(e, h) - qpos;
;                         if (d > 128 || d < -128) s[kt2][e] = -1e30f;
;                     }
;             }
;             if (fixed) {
;                 float ls = 0.f;
.Lr_go:
	s_add_i32 s47, s46, 2
	s_cmp_lt_u32 s47, s26
	s_cbranch_scc0 .Lr_nodma
	s_and_b32 s55, s47, 3
	s_lshl_b32 s55, s55, 14
	s_cmp_lt_u32 s47, s21
	s_cselect_b64 s[0:1], -1, 0
	s_sub_i32 s17, s47, s21
	s_min_u32 s17, s47, s17
	s_and_b64 s[0:1], s[0:1], exec
	s_cselect_b32 s0, s20, s27
	s_cselect_b32 s1, s25, s41
	s_cselect_b32 s48, s24, s40
	s_lshl_b32 s49, s17, 6
	s_add_i32 s49, s49, s0
	s_lshl_b32 s0, s17, 7
	s_add_u32 s0, s48, s0
	s_addc_u32 s1, s1, 0
	s_mul_hi_i32 s17, s49, 0x1a80
	s_mulk_i32 s49, 0x1a80
	s_add_u32 s48, s42, s49
	s_addc_u32 s49, s43, s17
	v_add_u32_e32 v2, v206, v222
	s_add_i32 m0, s98, s55
	v_add_u32_e32 v3, v208, v222
	global_load_lds_dwordx4 v2, s[48:49]
	s_add_i32 m0, m0, 0x2000
	v_add_u32_e32 v5, v210, v224
	global_load_lds_dwordx4 v3, s[0:1]
	s_add_i32 m0, s99, s55
	v_add_u32_e32 v6, v212, v224
	global_load_lds_dwordx4 v5, s[48:49]
	s_add_i32 m0, m0, 0x2000
	s_nop 0
	global_load_lds_dwordx4 v6, s[0:1]
.Lr_nodma:
	s_and_b32 s17, s46, 3
	s_lshl_b32 s17, s17, 13
.Lr_body:
	v_lshl_add_u32 v226, s17, 1, v248
	v_lshl_add_u32 v5, v201, 1, v226
	v_lshl_add_u32 v6, v245, 1, v226
	ds_read_b128 v[112:115], v5
	ds_read_b128 v[116:119], v5 offset:4096
	v_lshl_add_u32 v223, v246, 1, v226
	ds_read_b128 v[120:123], v6
	ds_read_b128 v[124:127], v6 offset:4096
	v_lshl_add_u32 v225, v247, 1, v226
	ds_read_b128 v[128:131], v223
	ds_read_b128 v[132:135], v223 offset:4096
	ds_read_b128 v[136:139], v225
	ds_read_b128 v[140:143], v225 offset:4096
	v_mov_b32_e32 v2, 0
	v_mov_b32_e32 v3, 0
	v_mov_b32_e32 v12, s52
	v_mov_b32_e32 v13, 0
	v_mov_b32_e32 v14, 0
	v_mov_b32_e32 v15, 0
	v_mov_b32_e32 v8, v192
	v_mov_b32_e32 v9, 0
	v_mov_b32_e32 v10, 0
	v_mov_b32_e32 v11, 0
	s_waitcnt lgkmcnt(7)
	v_mfma_f32_32x32x16_bf16 v[96:111], v[112:115], v[176:179], 0
	s_waitcnt lgkmcnt(6)
	v_mfma_f32_32x32x16_bf16 v[80:95], v[116:119], v[176:179], 0
	s_waitcnt lgkmcnt(5)
	v_mfma_f32_32x32x16_bf16 v[96:111], v[120:123], v[180:183], v[96:111]
	s_waitcnt lgkmcnt(4)
	v_mfma_f32_32x32x16_bf16 v[80:95], v[124:127], v[180:183], v[80:95]
	ds_read_b128 v[112:115], v5 offset:8192
	ds_read_b128 v[116:119], v5 offset:12288
	v_mfma_f32_32x32x16_bf16 v[96:111], v[12:15], v[0:3], v[96:111]
	ds_read_b128 v[120:123], v6 offset:8192
	ds_read_b128 v[124:127], v6 offset:12288
	v_mfma_f32_32x32x16_bf16 v[80:95], v[12:15], v[0:3], v[80:95]
	s_waitcnt lgkmcnt(7)
	v_mfma_f32_32x32x16_bf16 v[144:159], v[128:131], v[184:187], 0
	s_waitcnt lgkmcnt(6)
	v_mfma_f32_32x32x16_bf16 v[160:175], v[132:135], v[184:187], 0
	s_waitcnt lgkmcnt(5)
	v_mfma_f32_32x32x16_bf16 v[144:159], v[136:139], v[188:191], v[144:159]
	s_waitcnt lgkmcnt(4)
	v_mfma_f32_32x32x16_bf16 v[160:175], v[140:143], v[188:191], v[160:175]
	ds_read_b128 v[128:131], v223 offset:8192
	ds_read_b128 v[132:135], v223 offset:12288
	v_exp_f32_e32 v96, v96
	v_exp_f32_e32 v97, v97
	v_exp_f32_e32 v98, v98
	v_exp_f32_e32 v99, v99
	v_mfma_f32_32x32x16_bf16 v[144:159], v[12:15], v[8:11], v[144:159]
	ds_read_b128 v[136:139], v225 offset:8192
	ds_read_b128 v[140:143], v225 offset:12288
	v_exp_f32_e32 v100, v100
	v_exp_f32_e32 v101, v101
	v_pk_add_f32 v[2:3], v[96:97], v[98:99]
	v_exp_f32_e32 v102, v102
	v_exp_f32_e32 v103, v103
	v_pk_add_f32 v[2:3], v[2:3], v[100:101]
	v_mfma_f32_32x32x16_bf16 v[160:175], v[12:15], v[8:11], v[160:175]
	v_exp_f32_e32 v104, v104
	v_exp_f32_e32 v105, v105
	v_pk_add_f32 v[2:3], v[2:3], v[102:103]
	v_exp_f32_e32 v106, v106
	v_exp_f32_e32 v107, v107
	v_pk_add_f32 v[2:3], v[2:3], v[104:105]
	v_exp_f32_e32 v108, v108
	v_exp_f32_e32 v109, v109
	v_pk_add_f32 v[2:3], v[2:3], v[106:107]
	v_exp_f32_e32 v110, v110
	v_exp_f32_e32 v111, v111
	v_pk_add_f32 v[2:3], v[2:3], v[108:109]
	v_exp_f32_e32 v80, v80
	v_exp_f32_e32 v81, v81
	v_pk_add_f32 v[2:3], v[2:3], v[110:111]
	v_exp_f32_e32 v82, v82
	v_exp_f32_e32 v83, v83
	v_pk_add_f32 v[2:3], v[2:3], v[80:81]
	v_exp_f32_e32 v84, v84
	v_exp_f32_e32 v85, v85
	v_pk_add_f32 v[2:3], v[2:3], v[82:83]
	v_exp_f32_e32 v86, v86
	v_exp_f32_e32 v87, v87
	v_pk_add_f32 v[2:3], v[2:3], v[84:85]
	v_exp_f32_e32 v88, v88
	v_exp_f32_e32 v89, v89
	v_pk_add_f32 v[2:3], v[2:3], v[86:87]
	v_exp_f32_e32 v90, v90
	v_exp_f32_e32 v91, v91
	v_pk_add_f32 v[2:3], v[2:3], v[88:89]
	v_exp_f32_e32 v92, v92
	v_exp_f32_e32 v93, v93
	v_pk_add_f32 v[2:3], v[2:3], v[90:91]
	v_exp_f32_e32 v94, v94
	v_exp_f32_e32 v95, v95
	v_pk_add_f32 v[2:3], v[2:3], v[92:93]
	v_mov_b32_e32 v96, v96
	v_pk_add_f32 v[2:3], v[2:3], v[94:95]
	v_cvt_pk_bf16_f32 v96, v96, v97
	v_cvt_pk_bf16_f32 v97, v98, v99
	v_cvt_pk_bf16_f32 v98, v100, v101
	v_cvt_pk_bf16_f32 v99, v102, v103
	v_cvt_pk_bf16_f32 v100, v104, v105
	v_cvt_pk_bf16_f32 v101, v106, v107
	v_cvt_pk_bf16_f32 v102, v108, v109
	v_cvt_pk_bf16_f32 v103, v110, v111
	v_cvt_pk_bf16_f32 v80, v80, v81
	v_cvt_pk_bf16_f32 v81, v82, v83
	v_cvt_pk_bf16_f32 v82, v84, v85
	v_cvt_pk_bf16_f32 v83, v86, v87
	v_cvt_pk_bf16_f32 v84, v88, v89
	v_cvt_pk_bf16_f32 v85, v90, v91
	v_cvt_pk_bf16_f32 v86, v92, v93
	v_cvt_pk_bf16_f32 v87, v94, v95
	v_add_f32_e32 v2, v2, v3
	v_add_f32_e32 v194, v194, v2
	s_waitcnt lgkmcnt(7)
; #define MFMA(a, b, c) __builtin_amdgcn_mfma_f32_32x32x16_bf16((a), (b), (c), 0, 0, 0)
; template <int NS>
; DI void attn_item(const Params& p, int layer, char* smem, VBC& vc, int b, int hq, int qblk) {
;     ...
;             if (fixed) {
;                 float ls = 0.f;
; #pragma unroll
;                 for (int kt2 = 0; kt2 < 2; ++kt2)
; #pragma unroll
;                     for (int e = 0; e < 16; ++e) { const float pv = __builtin_amdgcn_exp2f(s[kt2][e]); s[kt2][e] = pv; ls += pv; }
;                 lrun[m] += ls;
;     ...
;             for (int kt2 = 0; kt2 < 2; ++kt2) { pf[kt2][0] = pack8(s[kt2], 0); pf[kt2][1] = pack8(s[kt2], 1); }
;         };
;         auto pvm = [&](const int m, const bf16x8 (&pf)[2][2]) {
;             __builtin_amdgcn_s_setprio(1);
; #pragma unroll
;             for (int kk = 0; kk < 4; ++kk)
; #pragma unroll
;                 for (int dvt = 0; dvt < 2; ++dvt) O[m][dvt] = MFMA(ld8(cV + (dvt * 32 + r) * 64 + ((kk * 16) ^ hs16)), pf[kk >> 1][kk & 1], O[m][dvt]);
;             __builtin_amdgcn_s_setprio(0);
;         };
	v_mfma_f32_32x32x16_bf16 v[64:79], v[112:115], v[96:99], v[64:79]
	v_exp_f32_e32 v144, v144
	v_exp_f32_e32 v145, v145
	v_exp_f32_e32 v146, v146
	v_exp_f32_e32 v147, v147
	v_exp_f32_e32 v148, v148
	v_exp_f32_e32 v149, v149
	v_pk_add_f32 v[14:15], v[144:145], v[146:147]
	v_exp_f32_e32 v150, v150
	s_waitcnt lgkmcnt(6)
	v_mfma_f32_32x32x16_bf16 v[32:47], v[116:119], v[96:99], v[32:47]
	v_exp_f32_e32 v151, v151
	v_pk_add_f32 v[14:15], v[14:15], v[148:149]
	v_exp_f32_e32 v152, v152
	v_exp_f32_e32 v153, v153
	v_pk_add_f32 v[14:15], v[14:15], v[150:151]
	v_exp_f32_e32 v154, v154
	v_exp_f32_e32 v155, v155
	v_pk_add_f32 v[14:15], v[14:15], v[152:153]
	s_waitcnt lgkmcnt(5)
	v_mfma_f32_32x32x16_bf16 v[64:79], v[120:123], v[100:103], v[64:79]
	v_exp_f32_e32 v156, v156
	v_exp_f32_e32 v157, v157
	v_pk_add_f32 v[14:15], v[14:15], v[154:155]
	v_exp_f32_e32 v158, v158
	v_exp_f32_e32 v159, v159
	v_pk_add_f32 v[14:15], v[14:15], v[156:157]
	v_exp_f32_e32 v160, v160
	v_exp_f32_e32 v161, v161
	s_waitcnt lgkmcnt(4)
	v_mfma_f32_32x32x16_bf16 v[32:47], v[124:127], v[100:103], v[32:47]
	v_pk_add_f32 v[14:15], v[14:15], v[158:159]
	v_exp_f32_e32 v162, v162
	v_exp_f32_e32 v163, v163
	v_pk_add_f32 v[14:15], v[14:15], v[160:161]
	v_exp_f32_e32 v164, v164
	v_exp_f32_e32 v165, v165
	v_pk_add_f32 v[14:15], v[14:15], v[162:163]
	v_exp_f32_e32 v166, v166
	s_waitcnt lgkmcnt(3)
	v_mfma_f32_32x32x16_bf16 v[64:79], v[128:131], v[80:83], v[64:79]
	v_exp_f32_e32 v167, v167
	v_pk_add_f32 v[14:15], v[14:15], v[164:165]
	v_exp_f32_e32 v168, v168
	v_exp_f32_e32 v169, v169
	v_pk_add_f32 v[14:15], v[14:15], v[166:167]
	v_exp_f32_e32 v170, v170
	v_exp_f32_e32 v171, v171
	v_pk_add_f32 v[14:15], v[14:15], v[168:169]
	s_waitcnt lgkmcnt(2)
	v_mfma_f32_32x32x16_bf16 v[32:47], v[132:135], v[80:83], v[32:47]
	v_exp_f32_e32 v172, v172
	v_exp_f32_e32 v173, v173
	v_pk_add_f32 v[14:15], v[14:15], v[170:171]
	v_exp_f32_e32 v174, v174
	v_exp_f32_e32 v175, v175
	v_pk_add_f32 v[14:15], v[14:15], v[172:173]
	v_mov_b32_e32 v144, v144
	v_pk_add_f32 v[14:15], v[14:15], v[174:175]
	s_waitcnt lgkmcnt(1)
	v_mfma_f32_32x32x16_bf16 v[64:79], v[136:139], v[84:87], v[64:79]
	s_waitcnt lgkmcnt(0)
	v_mfma_f32_32x32x16_bf16 v[32:47], v[140:143], v[84:87], v[32:47]
	v_cvt_pk_bf16_f32 v144, v144, v145
	v_cvt_pk_bf16_f32 v145, v146, v147
	v_cvt_pk_bf16_f32 v146, v148, v149
	v_cvt_pk_bf16_f32 v147, v150, v151
	v_cvt_pk_bf16_f32 v148, v152, v153
	v_cvt_pk_bf16_f32 v149, v154, v155
	v_cvt_pk_bf16_f32 v150, v156, v157
	v_cvt_pk_bf16_f32 v151, v158, v159
	v_cvt_pk_bf16_f32 v160, v160, v161
	v_cvt_pk_bf16_f32 v161, v162, v163
	v_cvt_pk_bf16_f32 v162, v164, v165
	v_cvt_pk_bf16_f32 v163, v166, v167
	v_cvt_pk_bf16_f32 v164, v168, v169
	v_cvt_pk_bf16_f32 v165, v170, v171
	v_cvt_pk_bf16_f32 v166, v172, v173
	v_cvt_pk_bf16_f32 v167, v174, v175
	v_add_f32_e32 v193, v14, v15
	v_add_f32_e32 v4, v4, v193
	s_nop 1
	v_mfma_f32_32x32x16_bf16 v[48:63], v[112:115], v[144:147], v[48:63]
	v_mfma_f32_32x32x16_bf16 v[16:31], v[116:119], v[144:147], v[16:31]
	v_mfma_f32_32x32x16_bf16 v[48:63], v[120:123], v[148:151], v[48:63]
	v_mfma_f32_32x32x16_bf16 v[16:31], v[124:127], v[148:151], v[16:31]
	v_mfma_f32_32x32x16_bf16 v[48:63], v[128:131], v[160:163], v[48:63]
	v_mfma_f32_32x32x16_bf16 v[16:31], v[132:135], v[160:163], v[16:31]
	v_mfma_f32_32x32x16_bf16 v[48:63], v[136:139], v[164:167], v[48:63]
	v_mfma_f32_32x32x16_bf16 v[16:31], v[140:143], v[164:167], v[16:31]
	s_cmp_lg_u32 s46, s44
	s_cbranch_scc0 .Lr_exit
	s_add_i32 s46, s46, 1
	s_branch .Lr_loop

; DI void phase_ln(const Params& p, int layer, const VBC& vc) {
;     ...
;         for (int j = 0; j < 4; ++j) {
;             const int n = lane * 4 + 256 * j;
;             float4 gv = *(const float4*)(g + n), bv = *(const float4*)(bta + n), o;
.Lln_pre:
	global_load_dwordx4 v[76:79], v[10:11], off
	global_load_dwordx4 v[80:83], v[10:11], off offset:1024
	global_load_dwordx4 v[84:87], v[10:11], off offset:2048
	global_load_dwordx4 v[88:91], v[10:11], off offset:3072
	global_load_dwordx4 v[92:95], v[12:13], off
	global_load_dwordx4 v[96:99], v[12:13], off offset:1024
	global_load_dwordx4 v[100:103], v[12:13], off offset:2048
	global_load_dwordx4 v[104:107], v[12:13], off offset:3072
	s_branch .LBB0_1377

; DI float wave_sum(float v) { for (int o = 32; o > 0; o >>= 1) v += __shfl_xor(v, o); return v; }
; DI void phase_ln(const Params& p, int layer, const VBC& vc) {
;     ...
;     for (int row = gw; row < nrows; row += nw) {
;         float* xr = row < NLAT ? p.out + (size_t)row * 1024 : (float*)(p.ws + OFF_XC) + (size_t)(row - NLAT) * 1024;
;         float4 v[4];
;         float s = 0.f;
; #pragma unroll
;         for (int j = 0; j < 4; ++j) { v[j] = *(const float4*)(xr + lane * 4 + 256 * j); s += v[j].x + v[j].y + v[j].z + v[j].w; }
;         const float mean = wave_sum(s) * (1.f / 1024.f);
;         float q = 0.f;
; #pragma unroll
;         for (int j = 0; j < 4; ++j) { v[j].x -= mean; v[j].y -= mean; v[j].z -= mean; v[j].w -= mean; q += v[j].x * v[j].x + v[j].y * v[j].y + v[j].z * v[j].z + v[j].w * v[j].w; }
;         const float rstd = rsqrtf(wave_sum(q) * (1.f / 1024.f) + LN_EPS);
;         const int r = row < NLAT ? (row >> 12) : 8;
;         const float* md = MOD + ((size_t)(layer + 1) * 9 + r) * 3072;
;         if (layer < DEPTH - 1 && lane == 0) ((float2*)(p.ws + OFF_STATS))[row] = make_float2(mean, rstd);
.LBB0_1377:
	v_readlane_b32 s0, v251, 39
	v_cmp_gt_i32_e32 vcc, s66, v6
	v_add_u32_e32 v0, 0xffff8000, v6
	v_readlane_b32 s1, v251, 40
	v_cndmask_b32_e32 v2, v0, v6, vcc
	v_mov_b32_e32 v4, s29
	v_mov_b32_e32 v0, s1
	v_cndmask_b32_e32 v3, 0, v7, vcc
	v_cndmask_b32_e32 v5, v0, v4, vcc
	v_mov_b32_e32 v0, s0
	v_mov_b32_e32 v4, s28
	v_cndmask_b32_e32 v4, v0, v4, vcc
	v_lshlrev_b64 v[2:3], 12, v[2:3]
	v_lshl_add_u64 v[2:3], v[4:5], 0, v[2:3]
	v_lshlrev_b32_e32 v0, 2, v8
	v_lshl_add_u64 v[24:25], v[2:3], 0, v[0:1]
	global_load_dwordx4 v[60:63], v[24:25], off
	global_load_dwordx4 v[64:67], v[24:25], off offset:1024
	global_load_dwordx4 v[68:71], v[24:25], off offset:2048
	global_load_dwordx4 v[72:75], v[24:25], off offset:3072
	s_andn2_b64 vcc, exec, s[4:5]
	s_cbranch_vccnz .Lln_nomd
	v_min_i32_e32 v19, 0x8000, v6
	v_ashrrev_i32_e32 v30, 12, v19
	v_readlane_b32 s2, v251, 43
	v_ashrrev_i32_e32 v31, 31, v30
	v_readlane_b32 s3, v251, 44
	v_lshl_add_u64 v[30:31], v[30:31], 0, s[10:11]
	s_nop 1
	v_mov_b64_e32 v[38:39], s[2:3]
	v_mad_u64_u32 v[40:41], s[2:3], v30, s71, v[38:39]
	v_mad_i32_i24 v41, v31, s71, v41
	v_lshl_add_u64 v[40:41], v[40:41], 0, v[0:1]
	s_mov_b64 s[2:3], 0x1000
	v_lshl_add_u64 v[38:39], v[40:41], 0, s[2:3]
	global_load_dwordx4 v[108:111], v[40:41], off
	global_load_dwordx4 v[112:115], v[40:41], off offset:1024
	global_load_dwordx4 v[116:119], v[40:41], off offset:2048
	global_load_dwordx4 v[120:123], v[40:41], off offset:3072
	global_load_dwordx4 v[124:127], v[38:39], off
	global_load_dwordx4 v[128:131], v[38:39], off offset:1024
	global_load_dwordx4 v[132:135], v[38:39], off offset:2048
	global_load_dwordx4 v[136:139], v[38:39], off offset:3072
.Lln_nomd:
	s_waitcnt vmcnt(0)
	v_add_f32_e32 v142, v60, v64
	v_add_f32_e32 v143, v61, v65
	v_add_f32_e32 v144, v62, v66
	v_add_f32_e32 v145, v63, v67
	v_add_f32_e32 v142, v142, v68
	v_add_f32_e32 v143, v143, v69
	v_add_f32_e32 v144, v144, v70
	v_add_f32_e32 v145, v145, v71
	v_add_f32_e32 v142, v142, v72
	v_add_f32_e32 v143, v143, v73
	v_add_f32_e32 v144, v144, v74
	v_add_f32_e32 v145, v145, v75
	v_add_f32_e32 v142, v142, v143
	v_add_f32_e32 v144, v144, v145
	v_add_f32_e32 v19, v142, v144
	ds_bpermute_b32 v21, v9, v19
	s_waitcnt lgkmcnt(0)
	v_add_f32_e32 v19, v19, v21
	ds_bpermute_b32 v21, v46, v19
	s_waitcnt lgkmcnt(0)
	v_add_f32_e32 v19, v19, v21
	ds_bpermute_b32 v21, v47, v19
	s_waitcnt lgkmcnt(0)
	v_add_f32_e32 v19, v19, v21
	ds_bpermute_b32 v21, v48, v19
	s_waitcnt lgkmcnt(0)
	v_add_f32_e32 v19, v19, v21
	ds_bpermute_b32 v21, v49, v19
	s_waitcnt lgkmcnt(0)
	v_add_f32_e32 v19, v19, v21
	ds_bpermute_b32 v21, v50, v19
	s_waitcnt lgkmcnt(0)
	v_add_f32_e32 v19, v19, v21
	v_mul_f32_e32 v140, 0x3a800000, v19
	v_sub_f32_e32 v60, v60, v140
	v_sub_f32_e32 v61, v61, v140
	v_sub_f32_e32 v62, v62, v140
	v_sub_f32_e32 v63, v63, v140
	v_sub_f32_e32 v64, v64, v140
	v_sub_f32_e32 v65, v65, v140
	v_sub_f32_e32 v66, v66, v140
	v_sub_f32_e32 v67, v67, v140
	v_sub_f32_e32 v68, v68, v140
	v_sub_f32_e32 v69, v69, v140
	v_sub_f32_e32 v70, v70, v140
	v_sub_f32_e32 v71, v71, v140
	v_sub_f32_e32 v72, v72, v140
	v_sub_f32_e32 v73, v73, v140
	v_sub_f32_e32 v74, v74, v140
	v_sub_f32_e32 v75, v75, v140
	v_mul_f32_e32 v142, v60, v60
	v_mul_f32_e32 v143, v61, v61
	v_mul_f32_e32 v144, v62, v62
	v_mul_f32_e32 v145, v63, v63
	v_fmac_f32_e32 v142, v64, v64
	v_fmac_f32_e32 v143, v65, v65
	v_fmac_f32_e32 v144, v66, v66
	v_fmac_f32_e32 v145, v67, v67
	v_fmac_f32_e32 v142, v68, v68
	v_fmac_f32_e32 v143, v69, v69
	v_fmac_f32_e32 v144, v70, v70
	v_fmac_f32_e32 v145, v71, v71
	v_fmac_f32_e32 v142, v72, v72
	v_fmac_f32_e32 v143, v73, v73
	v_fmac_f32_e32 v144, v74, v74
	v_fmac_f32_e32 v145, v75, v75
	v_add_f32_e32 v142, v142, v143
	v_add_f32_e32 v144, v144, v145
	v_add_f32_e32 v19, v142, v144
	ds_bpermute_b32 v21, v9, v19
	s_waitcnt lgkmcnt(0)
	v_add_f32_e32 v19, v19, v21
	ds_bpermute_b32 v21, v46, v19
	s_waitcnt lgkmcnt(0)
	v_add_f32_e32 v19, v19, v21
	ds_bpermute_b32 v21, v47, v19
	s_waitcnt lgkmcnt(0)
	v_add_f32_e32 v19, v19, v21
	ds_bpermute_b32 v21, v48, v19
	s_waitcnt lgkmcnt(0)
	v_add_f32_e32 v19, v19, v21
	ds_bpermute_b32 v21, v49, v19
	s_waitcnt lgkmcnt(0)
	v_add_f32_e32 v19, v19, v21
	ds_bpermute_b32 v21, v50, v19
	s_waitcnt lgkmcnt(0)
	v_add_f32_e32 v19, v19, v21
	v_fmamk_f32 v2, v19, 0x3a800000, v229
	v_cmp_gt_f32_e32 vcc, s95, v2
	v_mul_f32_e32 v3, 0x4b800000, v2
	s_nop 0
	v_cndmask_b32_e32 v2, v2, v3, vcc
	v_rsq_f32_e32 v2, v2
	s_nop 0
	v_mul_f32_e32 v3, 0x45800000, v2
	v_cndmask_b32_e32 v141, v2, v3, vcc
	s_and_saveexec_b64 s[0:1], s[12:13]
	s_cbranch_execz .Lln_nostat
	v_lshl_add_u64 v[2:3], s[30:31], 0, v[14:15]
	v_add_co_u32_e32 v2, vcc, 0x1e423000, v2
	s_nop 1
	v_addc_co_u32_e32 v3, vcc, 0, v3, vcc
	global_store_dwordx2 v[2:3], v[140:141], off offset:512
; DI void st_bf4(u16* dst, float a, float b, float c, float d) { uint2 u = {pk2(a, b), pk2(c, d)}; *(uint2*)dst = u; }
; DI void phase_ln(const Params& p, int layer, const VBC& vc) {
;     ...
; #pragma unroll
;         for (int j = 0; j < 4; ++j) {
;             const int n = lane * 4 + 256 * j;
;             float4 gv = *(const float4*)(g + n), bv = *(const float4*)(bta + n), o;
;             o.x = v[j].x * rstd * gv.x + bv.x; o.y = v[j].y * rstd * gv.y + bv.y; o.z = v[j].z * rstd * gv.z + bv.z; o.w = v[j].w * rstd * gv.w + bv.w;
;             if (layer == DEPTH - 1) *(float4*)(xr + n) = o;
;             if (layer < DEPTH - 1) {
;                 float4 sh = *(const float4*)(md + n), sc = *(const float4*)(md + 1024 + n);
;                 st_bf4(H + (size_t)row * LDK + n, o.x * (1.f + sc.x) + sh.x, o.y * (1.f + sc.y) + sh.y, o.z * (1.f + sc.z) + sh.z, o.w * (1.f + sc.w) + sh.w);
;             }
;         }
.Lln_nostat:
	s_or_b64 exec, exec, s[0:1]
	v_mul_f32_e32 v60, v60, v141
	v_mul_f32_e32 v61, v61, v141
	v_mul_f32_e32 v62, v62, v141
	v_mul_f32_e32 v63, v63, v141
	v_mul_f32_e32 v64, v64, v141
	v_mul_f32_e32 v65, v65, v141
	v_mul_f32_e32 v66, v66, v141
	v_mul_f32_e32 v67, v67, v141
	v_mul_f32_e32 v68, v68, v141
	v_mul_f32_e32 v69, v69, v141
	v_mul_f32_e32 v70, v70, v141
	v_mul_f32_e32 v71, v71, v141
	v_mul_f32_e32 v72, v72, v141
	v_mul_f32_e32 v73, v73, v141
	v_mul_f32_e32 v74, v74, v141
	v_mul_f32_e32 v75, v75, v141
	v_fma_f32 v60, v60, v76, v92
	v_fma_f32 v61, v61, v77, v93
	v_fma_f32 v62, v62, v78, v94
	v_fma_f32 v63, v63, v79, v95
	v_fma_f32 v64, v64, v80, v96
	v_fma_f32 v65, v65, v81, v97
	v_fma_f32 v66, v66, v82, v98
	v_fma_f32 v67, v67, v83, v99
	v_fma_f32 v68, v68, v84, v100
	v_fma_f32 v69, v69, v85, v101
	v_fma_f32 v70, v70, v86, v102
	v_fma_f32 v71, v71, v87, v103
	v_fma_f32 v72, v72, v88, v104
	v_fma_f32 v73, v73, v89, v105
	v_fma_f32 v74, v74, v90, v106
	v_fma_f32 v75, v75, v91, v107
	s_andn2_b64 vcc, exec, s[14:15]
	s_cbranch_vccnz .Lln_nox
	global_store_dwordx4 v[24:25], v[60:63], off
	global_store_dwordx4 v[24:25], v[64:67], off offset:1024
	global_store_dwordx4 v[24:25], v[68:71], off offset:2048
	global_store_dwordx4 v[24:25], v[72:75], off offset:3072
.Lln_nox:
	s_andn2_b64 vcc, exec, s[4:5]
	s_cbranch_vccnz .LBB0_1376
	v_add_f32_e32 v124, 1.0, v124
	v_add_f32_e32 v125, 1.0, v125
	v_add_f32_e32 v126, 1.0, v126
	v_add_f32_e32 v127, 1.0, v127
	v_add_f32_e32 v128, 1.0, v128
	v_add_f32_e32 v129, 1.0, v129
	v_add_f32_e32 v130, 1.0, v130
	v_add_f32_e32 v131, 1.0, v131
	v_add_f32_e32 v132, 1.0, v132
	v_add_f32_e32 v133, 1.0, v133
	v_add_f32_e32 v134, 1.0, v134
	v_add_f32_e32 v135, 1.0, v135
	v_add_f32_e32 v136, 1.0, v136
	v_add_f32_e32 v137, 1.0, v137
	v_add_f32_e32 v138, 1.0, v138
	v_add_f32_e32 v139, 1.0, v139
	v_fma_f32 v60, v60, v124, v108
	v_fma_f32 v61, v61, v125, v109
	v_fma_f32 v62, v62, v126, v110
	v_fma_f32 v63, v63, v127, v111
	v_fma_f32 v64, v64, v128, v112
	v_fma_f32 v65, v65, v129, v113
	v_fma_f32 v66, v66, v130, v114
	v_fma_f32 v67, v67, v131, v115
	v_fma_f32 v68, v68, v132, v116
	v_fma_f32 v69, v69, v133, v117
	v_fma_f32 v70, v70, v134, v118
	v_fma_f32 v71, v71, v135, v119
	v_fma_f32 v72, v72, v136, v120
	v_fma_f32 v73, v73, v137, v121
	v_fma_f32 v74, v74, v138, v122
	v_fma_f32 v75, v75, v139, v123
	v_cvt_pk_bf16_f32 v146, v60, v61
	v_cvt_pk_bf16_f32 v147, v62, v63
	v_cvt_pk_bf16_f32 v148, v64, v65
	v_cvt_pk_bf16_f32 v149, v66, v67
	v_cvt_pk_bf16_f32 v150, v68, v69
	v_cvt_pk_bf16_f32 v151, v70, v71
	v_cvt_pk_bf16_f32 v152, v72, v73
	v_cvt_pk_bf16_f32 v153, v74, v75
	v_lshl_add_u64 v[30:31], s[30:31], 0, v[16:17]
	v_add_co_u32_e32 v4, vcc, 0x2a6f000, v30
	s_nop 1
	v_addc_co_u32_e32 v5, vcc, 0, v31, vcc
	global_store_dwordx2 v[4:5], v[146:147], off offset:512
	global_store_dwordx2 v[4:5], v[148:149], off offset:1024
	global_store_dwordx2 v[4:5], v[150:151], off offset:1536
	global_store_dwordx2 v[4:5], v[152:153], off offset:2048
	s_branch .LBB0_1376

; __global__ void __launch_bounds__(512, 2) hybrid_fwd(Params p, int lo, int hi) {
;     extern __shared__ __attribute__((aligned(16))) unsigned char dyn_lds[];
;     const int wid = __builtin_amdgcn_readfirstlane((int)(threadIdx.x >> 6));
	.amdhsa_kernel _Z10hybrid_fwd6Paramsii
		.amdhsa_group_segment_fixed_size 0
		.amdhsa_private_segment_fixed_size 0
		.amdhsa_kernarg_size 408
		.amdhsa_user_sgpr_count 2
		.amdhsa_user_sgpr_dispatch_ptr 0
		.amdhsa_user_sgpr_queue_ptr 0
		.amdhsa_user_sgpr_kernarg_segment_ptr 1
		.amdhsa_user_sgpr_dispatch_id 0
		.amdhsa_user_sgpr_kernarg_preload_length 0
		.amdhsa_user_sgpr_kernarg_preload_offset 0
		.amdhsa_user_sgpr_private_segment_size 0
		.amdhsa_uses_dynamic_stack 0
		.amdhsa_enable_private_segment 0
		.amdhsa_system_sgpr_workgroup_id_x 1
		.amdhsa_system_sgpr_workgroup_id_y 0
		.amdhsa_system_sgpr_workgroup_id_z 0
		.amdhsa_system_sgpr_workgroup_info 0
		.amdhsa_system_vgpr_workitem_id 2
		.amdhsa_next_free_vgpr 254
		.amdhsa_next_free_sgpr 102
		.amdhsa_accum_offset 256
		.amdhsa_reserve_vcc 1
		.amdhsa_float_round_mode_32 0
		.amdhsa_float_round_mode_16_64 0
		.amdhsa_float_denorm_mode_32 3
		.amdhsa_float_denorm_mode_16_64 3
		.amdhsa_dx10_clamp 1
		.amdhsa_ieee_mode 1
		.amdhsa_fp16_overflow 0
		.amdhsa_tg_split 0
		.amdhsa_exception_fp_ieee_invalid_op 0
		.amdhsa_exception_fp_denorm_src 0
		.amdhsa_exception_fp_ieee_div_zero 0
		.amdhsa_exception_fp_ieee_overflow 0
		.amdhsa_exception_fp_ieee_underflow 0
		.amdhsa_exception_fp_ieee_inexact 0
		.amdhsa_exception_int_div_zero 0
	.end_amdhsa_kernel

; __global__ void __launch_bounds__(512, 2) hybrid_fwd(Params p, int lo, int hi) {
;     extern __shared__ __attribute__((aligned(16))) unsigned char dyn_lds[];
;     const int wid = __builtin_amdgcn_readfirstlane((int)(threadIdx.x >> 6));
amdhsa.kernels:
  - .agpr_count:     0
    .args:
      - .offset:         0
        .size:           144
        .value_kind:     by_value
      - .offset:         144
        .size:           4
        .value_kind:     by_value
      - .offset:         148
        .size:           4
        .value_kind:     by_value
      - .offset:         152
        .size:           4
        .value_kind:     hidden_block_count_x
      - .offset:         156
        .size:           4
        .value_kind:     hidden_block_count_y
      - .offset:         160
        .size:           4
        .value_kind:     hidden_block_count_z
      - .offset:         164
        .size:           2
        .value_kind:     hidden_group_size_x
      - .offset:         166
        .size:           2
        .value_kind:     hidden_group_size_y
      - .offset:         168
        .size:           2
        .value_kind:     hidden_group_size_z
      - .offset:         170
        .size:           2
        .value_kind:     hidden_remainder_x
      - .offset:         172
        .size:           2
        .value_kind:     hidden_remainder_y
      - .offset:         174
        .size:           2
        .value_kind:     hidden_remainder_z
      - .offset:         192
        .size:           8
        .value_kind:     hidden_global_offset_x
      - .offset:         200
        .size:           8
        .value_kind:     hidden_global_offset_y
      - .offset:         208
        .size:           8
        .value_kind:     hidden_global_offset_z
      - .offset:         216
        .size:           2
        .value_kind:     hidden_grid_dims
      - .offset:         240
        .size:           8
        .value_kind:     hidden_multigrid_sync_arg
      - .offset:         272
        .size:           4
        .value_kind:     hidden_dynamic_lds_size
    .group_segment_fixed_size: 0
    .kernarg_segment_align: 8
    .kernarg_segment_size: 408
    .language:       OpenCL C
    .language_version:
      - 2
      - 0
    .max_flat_workgroup_size: 512
    .name:           _Z10hybrid_fwd6Paramsii
    .private_segment_fixed_size: 0
    .sgpr_count:     108
    .sgpr_spill_count: 224
    .symbol:         _Z10hybrid_fwd6Paramsii.kd
    .uniform_work_group_size: 1
    .uses_dynamic_stack: false
    .vgpr_count:     254
    .vgpr_spill_count: 0
    .wavefront_size: 64
